# narrow projection columns (phase 3): operand loads of each unrolled block issued together
# speedup vs baseline: 1.0071x; 1.0038x over previous
; #define LAS __attribute__((address_space(3)))
; __device__ __forceinline__ f32x4 mfma16(bf16x8 a, bf16x8 b, f32x4 c) { return __builtin_amdgcn_mfma_f32_16x16x32_bf16(a, b, c, 0, 0, 0); }
; __device__ __forceinline__ void narrow_cols_unit(LAS unsigned char* lds, int rb, const bf16_t* HB, const bf16_t* Btn, const u64* ssq, const float* b_f, float* LOGF, float* GA) {
;     ...
; #pragma unroll 8
;     for (int ks = 0; ks < 32; ++ks) {
;         const bf16x8 af = *(const bf16x8*)(arow + ks * 32), bf0 = *(const bf16x8*)(b0 + ks * 32), bf1 = *(const bf16x8*)(b1 + ks * 32);
;         acc0 = mfma16(bf0, af, acc0); acc1 = mfma16(bf1, af, acc1);
;     }
;     LAS f32x4* red = (LAS f32x4*)lds;
;     __syncthreads();
;     if (kh == 1) { red[(rg * 2 + 0) * 64 + lane] = acc0; red[(rg * 2 + 1) * 64 + lane] = acc1; }
.LBB0_529:
	v_lshl_add_u64 v[14:15], v[8:9], 0, s[12:13]
	v_add_co_u32_e32 v12, vcc, 0x7a00000, v14
	v_lshl_add_u64 v[30:31], v[10:11], 0, s[12:13]
	s_nop 0
	v_addc_co_u32_e32 v13, vcc, 0, v15, vcc
	v_add_co_u32_e32 v14, vcc, 0x7a10000, v14
	global_load_dwordx4 v[22:25], v[12:13], off
	s_nop 0
	v_addc_co_u32_e32 v15, vcc, 0, v15, vcc
	global_load_dwordx4 v[26:29], v[14:15], off
	global_load_dwordx4 v[18:21], v[30:31], off offset:-256
	global_load_dwordx4 v[32:35], v[30:31], off offset:-192
	global_load_dwordx4 v[36:39], v[12:13], off offset:64
	global_load_dwordx4 v[40:43], v[14:15], off offset:64
	global_load_dwordx4 v[44:47], v[30:31], off offset:-128
	global_load_dwordx4 v[48:51], v[12:13], off offset:128
	global_load_dwordx4 v[52:55], v[14:15], off offset:128
	global_load_dwordx4 v[56:59], v[30:31], off offset:-64
	global_load_dwordx4 v[60:63], v[12:13], off offset:192
	global_load_dwordx4 v[64:67], v[14:15], off offset:192
	global_load_dwordx4 v[68:71], v[30:31], off
	global_load_dwordx4 v[72:75], v[12:13], off offset:256
	global_load_dwordx4 v[76:79], v[14:15], off offset:256
	global_load_dwordx4 v[80:83], v[30:31], off offset:64
	global_load_dwordx4 v[84:87], v[12:13], off offset:320
	global_load_dwordx4 v[88:91], v[14:15], off offset:320
	global_load_dwordx4 v[92:95], v[30:31], off offset:128
	global_load_dwordx4 v[96:99], v[12:13], off offset:384
	global_load_dwordx4 v[100:103], v[14:15], off offset:384
	global_load_dwordx4 v[104:107], v[30:31], off offset:192
	global_load_dwordx4 v[108:111], v[12:13], off offset:448
	global_load_dwordx4 v[112:115], v[14:15], off offset:448
	s_add_u32 s12, s12, 0x200
	s_addc_u32 s13, s13, 0
	s_cmpk_eq_i32 s12, 0x800
	s_waitcnt vmcnt(21)
	v_mfma_f32_16x16x32_bf16 v[4:7], v[22:25], v[18:21], v[4:7]
	v_mfma_f32_16x16x32_bf16 v[0:3], v[26:29], v[18:21], v[0:3]
	s_waitcnt vmcnt(20)
	s_nop 1
	v_mov_b64_e32 v[18:19], v[32:33]
	v_mov_b64_e32 v[20:21], v[34:35]
	s_nop 1
	s_waitcnt vmcnt(19)
	s_nop 1
	v_mov_b64_e32 v[22:23], v[36:37]
	v_mov_b64_e32 v[24:25], v[38:39]
	s_nop 1
	s_waitcnt vmcnt(18)
	s_nop 1
	v_mov_b64_e32 v[26:27], v[40:41]
	v_mov_b64_e32 v[28:29], v[42:43]
	s_nop 1
	v_mfma_f32_16x16x32_bf16 v[4:7], v[22:25], v[18:21], v[4:7]
	v_mfma_f32_16x16x32_bf16 v[0:3], v[26:29], v[18:21], v[0:3]
	s_waitcnt vmcnt(17)
	s_nop 1
	v_mov_b64_e32 v[18:19], v[44:45]
	v_mov_b64_e32 v[20:21], v[46:47]
	s_nop 1
	s_waitcnt vmcnt(16)
	s_nop 1
	v_mov_b64_e32 v[22:23], v[48:49]
	v_mov_b64_e32 v[24:25], v[50:51]
	s_nop 1
	s_waitcnt vmcnt(15)
	s_nop 1
	v_mov_b64_e32 v[26:27], v[52:53]
	v_mov_b64_e32 v[28:29], v[54:55]
	s_nop 1
	v_mfma_f32_16x16x32_bf16 v[4:7], v[22:25], v[18:21], v[4:7]
	v_mfma_f32_16x16x32_bf16 v[0:3], v[26:29], v[18:21], v[0:3]
	s_waitcnt vmcnt(14)
	s_nop 1
	v_mov_b64_e32 v[18:19], v[56:57]
	v_mov_b64_e32 v[20:21], v[58:59]
	s_nop 1
	s_waitcnt vmcnt(13)
	s_nop 1
	v_mov_b64_e32 v[22:23], v[60:61]
	v_mov_b64_e32 v[24:25], v[62:63]
	s_nop 1
	s_waitcnt vmcnt(12)
	s_nop 1
	v_mov_b64_e32 v[26:27], v[64:65]
	v_mov_b64_e32 v[28:29], v[66:67]
	s_nop 1
	v_mfma_f32_16x16x32_bf16 v[4:7], v[22:25], v[18:21], v[4:7]
	v_mfma_f32_16x16x32_bf16 v[0:3], v[26:29], v[18:21], v[0:3]
	s_waitcnt vmcnt(11)
	s_nop 1
	v_mov_b64_e32 v[18:19], v[68:69]
	v_mov_b64_e32 v[20:21], v[70:71]
	s_nop 1
	s_waitcnt vmcnt(10)
	s_nop 1
	v_mov_b64_e32 v[22:23], v[72:73]
	v_mov_b64_e32 v[24:25], v[74:75]
	s_nop 1
	s_waitcnt vmcnt(9)
	s_nop 1
	v_mov_b64_e32 v[26:27], v[76:77]
	v_mov_b64_e32 v[28:29], v[78:79]
	s_nop 1
	v_mfma_f32_16x16x32_bf16 v[4:7], v[22:25], v[18:21], v[4:7]
	v_mfma_f32_16x16x32_bf16 v[0:3], v[26:29], v[18:21], v[0:3]
	s_waitcnt vmcnt(8)
	s_nop 1
	v_mov_b64_e32 v[18:19], v[80:81]
	v_mov_b64_e32 v[20:21], v[82:83]
	s_nop 1
	s_waitcnt vmcnt(7)
	s_nop 1
	v_mov_b64_e32 v[22:23], v[84:85]
	v_mov_b64_e32 v[24:25], v[86:87]
	s_nop 1
	s_waitcnt vmcnt(6)
	s_nop 1
	v_mov_b64_e32 v[26:27], v[88:89]
	v_mov_b64_e32 v[28:29], v[90:91]
	s_nop 1
	v_mfma_f32_16x16x32_bf16 v[4:7], v[22:25], v[18:21], v[4:7]
	v_mfma_f32_16x16x32_bf16 v[0:3], v[26:29], v[18:21], v[0:3]
	s_waitcnt vmcnt(5)
	s_nop 1
	v_mov_b64_e32 v[18:19], v[92:93]
	v_mov_b64_e32 v[20:21], v[94:95]
	s_nop 1
	s_waitcnt vmcnt(4)
	s_nop 1
	v_mov_b64_e32 v[22:23], v[96:97]
	v_mov_b64_e32 v[24:25], v[98:99]
	s_nop 1
	s_waitcnt vmcnt(3)
	s_nop 1
	v_mov_b64_e32 v[26:27], v[100:101]
	v_mov_b64_e32 v[28:29], v[102:103]
	s_nop 1
	v_mfma_f32_16x16x32_bf16 v[4:7], v[22:25], v[18:21], v[4:7]
	v_mfma_f32_16x16x32_bf16 v[0:3], v[26:29], v[18:21], v[0:3]
	s_waitcnt vmcnt(2)
	s_nop 1
	v_mov_b64_e32 v[18:19], v[104:105]
	v_mov_b64_e32 v[20:21], v[106:107]
	s_nop 1
	s_waitcnt vmcnt(1)
	s_nop 1
	v_mov_b64_e32 v[22:23], v[108:109]
	v_mov_b64_e32 v[24:25], v[110:111]
	s_nop 1
	s_nop 0
	s_waitcnt vmcnt(0)
	s_nop 1
	v_mov_b64_e32 v[12:13], v[112:113]
	v_mov_b64_e32 v[14:15], v[114:115]
	s_nop 1
	v_mfma_f32_16x16x32_bf16 v[4:7], v[22:25], v[18:21], v[4:7]
	v_mfma_f32_16x16x32_bf16 v[0:3], v[12:15], v[18:21], v[0:3]
	s_cbranch_scc0 .LBB0_529
	v_and_b32_e32 v15, 63, v17
	s_cmp_eq_u32 s25, 1
	s_barrier
	s_cbranch_scc0 .LBB0_532
	s_lshl_b32 s12, s24, 11
	s_add_i32 s12, s12, 0
	v_lshl_add_u32 v8, v15, 4, s12
	ds_write_b128 v8, v[4:7]
	ds_write_b128 v8, v[0:3] offset:1024
